# baseline (speedup 1.0000x reference)
; __device__ __forceinline__ uint2 pk4(f32x4 v) { return make_uint2(cvt_pk_bf16(v[0], v[1]), cvt_pk_bf16(v[2], v[3])); }
; __device__ __forceinline__ void cvt_range(const float* __restrict__ src, bf16_t* __restrict__ dst, size_t n8) {
;     for (size_t i = (size_t)blockIdx.x * 512 + threadIdx.x; i < n8; i += (size_t)gridDim.x * 512) {
;         const f32x4 a = *(const f32x4*)(src + i * 8), b = *(const f32x4*)(src + i * 8 + 4);
;         const uint2 lo = pk4(a), hi = pk4(b);
;         *(uint4*)(dst + i * 8) = make_uint4(lo.x, lo.y, hi.x, hi.y);
;     }
; }
; __device__ void phase_prep(const Params& P, unsigned char* smem) {
;     ...
;     cvt_range(P.in[I_SK], (bf16_t*)(ws + O_SKB), (size_t)262144 / 8);
.LBB0_19:
	s_or_b64 exec, exec, s[4:5]
	s_mov_b64 s[4:5], 0x8000
	v_cmp_gt_u64_e32 vcc, s[4:5], v[2:3]
	s_and_saveexec_b64 s[4:5], vcc
	s_cbranch_execz .LBB0_22
	s_lshl_b64 s[6:7], s[2:3], 13
	s_add_u32 s6, s90, s6
	v_mov_b32_e32 v5, 0
	s_addc_u32 s7, s91, s7
	v_lshl_add_u64 v[8:9], s[6:7], 0, v[4:5]
	s_mov_b64 s[6:7], 0x4500000
	v_lshl_add_u64 v[8:9], v[8:9], 0, s[6:7]
	v_bfe_u32 v254, v144, 2, 1
	v_bfe_u32 v255, v144, 3, 1
	v_lshlrev_b32_e32 v254, 6, v254
	v_lshl_add_u32 v254, v255, 7, v254
	v_bfe_u32 v255, v144, 4, 1
	v_mul_u32_u24_e32 v255, 0xc0, v255
	v_sub_u32_e32 v254, v254, v255
	v_ashrrev_i32_e32 v255, 31, v254
	v_lshl_add_u64 v[8:9], v[254:255], 0, v[8:9]
	s_lshl_b64 s[6:7], s[8:9], 13
	s_lshl_b64 s[10:11], s[2:3], 14
	s_add_u32 s10, s42, s10
	v_mov_b32_e32 v7, v5
	s_addc_u32 s11, s43, s11
	v_lshl_add_u64 v[6:7], s[10:11], 0, v[6:7]
	v_lshl_add_u64 v[6:7], v[6:7], 0, 16
	s_lshl_b64 s[10:11], s[8:9], 14
	s_mov_b64 s[12:13], 0
	s_mov_b64 s[14:15], 0x7fff
	v_mov_b64_e32 v[10:11], v[2:3]

; __device__ __forceinline__ f32x4 mfma16(bf16x8 a, bf16x8 b, f32x4 c) { return __builtin_amdgcn_mfma_f32_16x16x32_bf16(a, b, c, 0, 0, 0); }
; __device__ void phase_peer(const Params& P, unsigned char* smem) {
;     ...
;                 const int hp_ = h * 2 + (p & 1);
;                 const bf16_t* qp_ = QP + (size_t)(tok0 + l15) * D + hp_ * 128 + l4 * 8;
;                 const bf16_t* kp_ = SKB + ((size_t)hp_ * 128 + l15) * 128 + l4 * 8;
;                 f32x4 acc[2][8];
; #pragma unroll
;                 for (int th = 0; th < 2; ++th)
; #pragma unroll
;                     for (int tn = 0; tn < 8; ++tn) acc[th][tn] = (f32x4){0.f, 0.f, 0.f, 0.f};
; #pragma unroll
;                 for (int ks = 0; ks < 4; ++ks) {
;                     bf16x8 qf[2], kf[8];
; #pragma unroll
;                     for (int th = 0; th < 2; ++th) qf[th] = *(const bf16x8*)(qp_ + (size_t)th * 16 * D + ks * 32);
; #pragma unroll
;                     for (int tn = 0; tn < 8; ++tn) kf[tn] = *(const bf16x8*)(kp_ + tn * 16 * 128 + ks * 32);
; #pragma unroll
;                     for (int th = 0; th < 2; ++th)
; #pragma unroll
;                         for (int tn = 0; tn < 8; ++tn) acc[th][tn] = mfma16(kf[tn], qf[th], acc[th][tn]);
.LBB0_961:
	v_or_b32_e32 v0, s76, v108
	v_lshlrev_b32_e32 v48, 8, v0
	v_lshl_add_u64 v[216:217], v[40:41], 0, v[48:49]
	v_lshl_or_b32 v48, v0, 15, v154
	v_add_co_u32_e32 v244, vcc, 0x10000, v216
	v_lshl_add_u64 v[208:209], v[52:53], 0, v[48:49]
	v_bfe_i32 v254, v144, 0, 1
	v_and_b32_e32 v254, 0xffffff40, v254
	v_ashrrev_i32_e32 v255, 31, v254
	v_lshl_add_u64 v[208:209], v[254:255], 0, v[208:209]
	s_nop 0
	v_addc_co_u32_e32 v245, vcc, 0, v217, vcc
	v_add_co_u32_e32 v204, vcc, s29, v208
	s_mov_b64 s[18:19], vcc
	v_add_co_u32_e32 v228, vcc, s49, v208
	global_load_dwordx4 v[0:3], v[216:217], off offset:-2048
	s_nop 0
	v_addc_co_u32_e32 v229, vcc, 0, v209, vcc
	v_add_co_u32_e32 v236, vcc, s52, v208
	s_mov_b64 s[0:1], vcc
	v_add_co_u32_e32 v212, vcc, s53, v208
	s_mov_b64 s[20:21], vcc
	v_add_co_u32_e32 v220, vcc, s54, v208
	s_mov_b64 s[22:23], vcc
	v_add_co_u32_e32 v246, vcc, s55, v208
	s_mov_b64 s[24:25], vcc
	v_add_co_u32_e32 v232, vcc, s56, v208
	s_waitcnt lgkmcnt(14)
	global_load_dwordx4 v[4:7], v[244:245], off offset:-2048
	s_waitcnt lgkmcnt(11)
	global_load_dwordx4 v[8:11], v[208:209], off
	v_addc_co_u32_e32 v233, vcc, 0, v209, vcc
	v_addc_co_u32_e64 v213, vcc, 0, v209, s[20:21]
	v_addc_co_u32_e64 v247, vcc, 0, v209, s[24:25]
	v_addc_co_u32_e64 v205, vcc, 0, v209, s[18:19]
	s_waitcnt lgkmcnt(7)
	global_load_dwordx4 v[12:15], v[228:229], off offset:-4096
	global_load_dwordx4 v[16:19], v[216:217], off offset:-1920
	s_waitcnt lgkmcnt(3)
	global_load_dwordx4 v[20:23], v[208:209], off offset:128
	s_waitcnt lgkmcnt(1)
	global_load_dwordx4 v[24:27], v[244:245], off offset:-1920
	s_waitcnt lgkmcnt(0)
	global_load_dwordx4 v[28:31], v[232:233], off offset:384
	global_load_dwordx4 v[44:47], v[228:229], off
	global_load_dwordx4 v[66:69], v[228:229], off offset:128
	global_load_dwordx4 v[74:77], v[212:213], off offset:-4096
	global_load_dwordx4 v[78:81], v[212:213], off
	global_load_dwordx4 v[90:93], v[246:247], off offset:-4096
	global_load_dwordx4 v[94:97], v[246:247], off
	global_load_dwordx4 v[98:101], v[212:213], off offset:384
	global_load_dwordx4 v[168:171], v[204:205], off offset:128
	global_load_dwordx4 v[172:175], v[232:233], off
	v_addc_co_u32_e64 v237, vcc, 0, v209, s[0:1]
	v_addc_co_u32_e64 v221, vcc, 0, v209, s[22:23]
	global_load_dwordx4 v[160:163], v[246:247], off offset:128
	global_load_dwordx4 v[176:179], v[236:237], off offset:128
	global_load_dwordx4 v[180:183], v[204:205], off offset:256
	global_load_dwordx4 v[184:187], v[212:213], off offset:128
	global_load_dwordx4 v[188:191], v[220:221], off offset:128
	global_load_dwordx4 v[192:195], v[220:221], off offset:384
	global_load_dwordx4 v[196:199], v[232:233], off offset:128
	s_lshl_b32 s18, s76, 4
	s_waitcnt vmcnt(21)
	v_mfma_f32_16x16x32_bf16 v[32:35], v[8:11], v[0:3], 0
	v_mfma_f32_16x16x32_bf16 v[8:11], v[8:11], v[4:7], 0
	s_waitcnt vmcnt(20)
	v_mfma_f32_16x16x32_bf16 v[36:39], v[12:15], v[0:3], 0
	s_waitcnt vmcnt(15)
	v_mfma_f32_16x16x32_bf16 v[70:73], v[44:47], v[0:3], 0
	v_mfma_f32_16x16x32_bf16 v[12:15], v[12:15], v[4:7], 0
	v_mfma_f32_16x16x32_bf16 v[44:47], v[44:47], v[4:7], 0
	s_waitcnt vmcnt(13)
	v_mfma_f32_16x16x32_bf16 v[82:85], v[74:77], v[0:3], 0
	s_waitcnt vmcnt(12)
	v_mfma_f32_16x16x32_bf16 v[86:89], v[78:81], v[0:3], 0
	v_mfma_f32_16x16x32_bf16 v[74:77], v[74:77], v[4:7], 0
	v_mfma_f32_16x16x32_bf16 v[78:81], v[78:81], v[4:7], 0
	s_waitcnt vmcnt(11)
	v_mfma_f32_16x16x32_bf16 v[102:105], v[90:93], v[0:3], 0
	s_waitcnt vmcnt(10)
	v_mfma_f32_16x16x32_bf16 v[164:167], v[94:97], v[0:3], 0
	v_mfma_f32_16x16x32_bf16 v[90:93], v[90:93], v[4:7], 0
	v_mfma_f32_16x16x32_bf16 v[94:97], v[94:97], v[4:7], 0
	s_waitcnt vmcnt(7)
	v_mfma_f32_16x16x32_bf16 v[0:3], v[172:175], v[0:3], 0
	v_mfma_f32_16x16x32_bf16 v[4:7], v[172:175], v[4:7], 0
	global_load_dwordx4 v[172:175], v[208:209], off offset:256
	global_load_dwordx4 v[200:203], v[216:217], off offset:2048
	s_nop 0
	global_load_dwordx4 v[204:207], v[204:205], off offset:384
	s_nop 0
	global_load_dwordx4 v[208:211], v[208:209], off offset:384
	s_nop 0
	global_load_dwordx4 v[212:215], v[212:213], off offset:256
	s_nop 0
	global_load_dwordx4 v[216:219], v[216:217], off offset:2176
	s_nop 0
	global_load_dwordx4 v[220:223], v[220:221], off offset:256
	v_mfma_f32_16x16x32_bf16 v[32:35], v[20:23], v[16:19], v[32:35]
	global_load_dwordx4 v[224:227], v[228:229], off offset:256
	s_nop 0
	global_load_dwordx4 v[228:231], v[228:229], off offset:384
	s_nop 0
	global_load_dwordx4 v[232:235], v[232:233], off offset:256
	v_mfma_f32_16x16x32_bf16 v[36:39], v[168:171], v[16:19], v[36:39]
	v_mfma_f32_16x16x32_bf16 v[70:73], v[66:69], v[16:19], v[70:73]
	s_waitcnt vmcnt(15)
	v_mfma_f32_16x16x32_bf16 v[82:85], v[176:179], v[16:19], v[82:85]
	s_waitcnt vmcnt(13)
	v_mfma_f32_16x16x32_bf16 v[86:89], v[184:187], v[16:19], v[86:89]
	s_waitcnt vmcnt(12)
	v_mfma_f32_16x16x32_bf16 v[102:105], v[188:191], v[16:19], v[102:105]
	v_mfma_f32_16x16x32_bf16 v[164:167], v[160:163], v[16:19], v[164:167]
	s_waitcnt vmcnt(10)
	v_mfma_f32_16x16x32_bf16 v[0:3], v[196:199], v[16:19], v[0:3]
	global_load_dwordx4 v[16:19], v[236:237], off offset:256
	v_mfma_f32_16x16x32_bf16 v[12:15], v[168:171], v[24:27], v[12:15]
	global_load_dwordx4 v[168:171], v[244:245], off offset:2048
	s_nop 0
	global_load_dwordx4 v[236:239], v[236:237], off offset:384
	v_mfma_f32_16x16x32_bf16 v[8:11], v[20:23], v[24:27], v[8:11]
	global_load_dwordx4 v[20:23], v[246:247], off offset:256
	s_waitcnt vmcnt(12)
	v_mfma_f32_16x16x32_bf16 v[32:35], v[172:175], v[200:203], v[32:35]
	s_waitcnt vmcnt(8)
; __device__ __forceinline__ f32x4 mfma16(bf16x8 a, bf16x8 b, f32x4 c) { return __builtin_amdgcn_mfma_f32_16x16x32_bf16(a, b, c, 0, 0, 0); }
; __device__ __forceinline__ unsigned fkey(float f) { const unsigned u = __float_as_uint(f); return u ^ ((unsigned)((int)u >> 31) | 0x80000000u); }
; __device__ void phase_peer(const Params& P, unsigned char* smem) {
;     ...
;                     for (int th = 0; th < 2; ++th) qf[th] = *(const bf16x8*)(qp_ + (size_t)th * 16 * D + ks * 32);
; #pragma unroll
;                     for (int tn = 0; tn < 8; ++tn) kf[tn] = *(const bf16x8*)(kp_ + tn * 16 * 128 + ks * 32);
; #pragma unroll
;                     for (int th = 0; th < 2; ++th)
; #pragma unroll
;                         for (int tn = 0; tn < 8; ++tn) acc[th][tn] = mfma16(kf[tn], qf[th], acc[th][tn]);
;                 }
; #pragma unroll
;                 for (int th = 0; th < 2; ++th) {
;                     unsigned S32[32];
; #pragma unroll
;                     for (int tn = 0; tn < 8; ++tn)
; #pragma unroll
;                         for (int jj = 0; jj < 4; ++jj) S32[tn * 4 + jj] = (fkey(acc[th][tn][jj]) & ~127u) | (unsigned)(tn * 16 + l4 * 4 + jj);
	v_mfma_f32_16x16x32_bf16 v[240:243], v[208:211], v[216:219], v[32:35]
	s_nop 5
	global_load_dwordx4 v[32:35], v[244:245], off offset:2176
	s_nop 0
	global_load_dwordx4 v[244:247], v[246:247], off offset:384
	v_ashrrev_i32_e32 v48, 31, v240
	v_mfma_f32_16x16x32_bf16 v[36:39], v[180:183], v[200:203], v[36:39]
	v_bitop3_b32 v48, v48, v240, s57 bitop3:0x36
	v_ashrrev_i32_e32 v240, 31, v241
	v_and_or_b32 v48, v48, s58, v109
	v_mfma_f32_16x16x32_bf16 v[36:39], v[204:207], v[216:219], v[36:39]
	s_waitcnt vmcnt(8)
	v_mfma_f32_16x16x32_bf16 v[70:73], v[224:227], v[200:203], v[70:73]
	v_mfma_f32_16x16x32_bf16 v[44:47], v[66:69], v[24:27], v[44:47]
	v_mfma_f32_16x16x32_bf16 v[66:69], v[176:179], v[24:27], v[74:77]
	s_nop 3
	v_ashrrev_i32_e32 v179, 31, v36
	v_bitop3_b32 v36, v179, v36, s57 bitop3:0x36
	v_and_or_b32 v179, v36, s58, v118
	v_bitop3_b32 v74, v240, v241, s57 bitop3:0x36
	v_and_or_b32 v176, v74, s58, v115
	v_ashrrev_i32_e32 v74, 31, v242
	v_bitop3_b32 v74, v74, v242, s57 bitop3:0x36
	s_waitcnt vmcnt(7)
	v_mfma_f32_16x16x32_bf16 v[70:73], v[228:231], v[216:219], v[70:73]
	v_and_or_b32 v177, v74, s58, v116
	v_ashrrev_i32_e32 v74, 31, v243
	v_ashrrev_i32_e32 v36, 31, v37
	v_bitop3_b32 v74, v74, v243, s57 bitop3:0x36
	v_bitop3_b32 v36, v36, v37, s57 bitop3:0x36
	v_and_or_b32 v178, v74, s58, v117
	v_mfma_f32_16x16x32_bf16 v[74:77], v[184:187], v[24:27], v[78:81]
	v_mfma_f32_16x16x32_bf16 v[78:81], v[188:191], v[24:27], v[90:93]
	s_nop 2
	v_and_or_b32 v90, v36, s58, v119
	v_ashrrev_i32_e32 v36, 31, v38
	v_bitop3_b32 v36, v36, v38, s57 bitop3:0x36
	v_ashrrev_i32_e32 v93, 31, v70
	v_and_or_b32 v91, v36, s58, v120
	v_ashrrev_i32_e32 v36, 31, v39
	v_bitop3_b32 v70, v93, v70, s57 bitop3:0x36
	v_bitop3_b32 v36, v36, v39, s57 bitop3:0x36
	v_and_or_b32 v93, v70, s58, v122
	v_ashrrev_i32_e32 v70, 31, v71
	v_and_or_b32 v92, v36, s58, v121
	v_mfma_f32_16x16x32_bf16 v[36:39], v[160:163], v[24:27], v[94:97]
	v_mfma_f32_16x16x32_bf16 v[4:7], v[196:199], v[24:27], v[4:7]
	v_bitop3_b32 v24, v70, v71, s57 bitop3:0x36
	s_nop 0
	v_and_or_b32 v94, v24, s58, v123
	v_ashrrev_i32_e32 v70, 31, v72
	s_waitcnt vmcnt(5)
	v_mfma_f32_16x16x32_bf16 v[24:27], v[16:19], v[200:203], v[82:85]
	v_bitop3_b32 v70, v70, v72, s57 bitop3:0x36
	v_and_or_b32 v95, v70, s58, v124
	v_ashrrev_i32_e32 v70, 31, v73
	s_waitcnt vmcnt(3)
	v_mfma_f32_16x16x32_bf16 v[24:27], v[236:239], v[216:219], v[24:27]
	v_bitop3_b32 v70, v70, v73, s57 bitop3:0x36
	v_and_or_b32 v96, v70, s58, v125
	v_mfma_f32_16x16x32_bf16 v[70:73], v[212:215], v[200:203], v[86:89]
	v_mfma_f32_16x16x32_bf16 v[70:73], v[98:101], v[216:219], v[70:73]
	s_nop 3
	v_ashrrev_i32_e32 v82, 31, v24
	v_bitop3_b32 v24, v82, v24, s57 bitop3:0x36
	v_and_or_b32 v97, v24, s58, v126
	v_ashrrev_i32_e32 v24, 31, v25
	v_bitop3_b32 v24, v24, v25, s57 bitop3:0x36
	v_mfma_f32_16x16x32_bf16 v[82:85], v[220:223], v[200:203], v[102:105]
	s_nop 2
	v_and_or_b32 v102, v24, s58, v127
	v_ashrrev_i32_e32 v24, 31, v26
	v_bitop3_b32 v24, v24, v26, s57 bitop3:0x36
	v_and_or_b32 v103, v24, s58, v128
	v_ashrrev_i32_e32 v24, 31, v27
	v_bitop3_b32 v24, v24, v27, s57 bitop3:0x36
	v_and_or_b32 v104, v24, s58, v129
	v_ashrrev_i32_e32 v24, 31, v70
	v_bitop3_b32 v24, v24, v70, s57 bitop3:0x36
	v_and_or_b32 v105, v24, s58, v130
	v_ashrrev_i32_e32 v24, 31, v71
	v_bitop3_b32 v24, v24, v71, s57 bitop3:0x36
	v_and_or_b32 v160, v24, s58, v131
	v_ashrrev_i32_e32 v24, 31, v72
	v_bitop3_b32 v24, v24, v72, s57 bitop3:0x36
	v_and_or_b32 v161, v24, s58, v132
	v_mfma_f32_16x16x32_bf16 v[24:27], v[192:195], v[216:219], v[82:85]
	v_ashrrev_i32_e32 v70, 31, v73
	v_bitop3_b32 v70, v70, v73, s57 bitop3:0x36
	s_nop 0
	v_and_or_b32 v82, v70, s58, v133
	s_waitcnt vmcnt(2)
	v_mfma_f32_16x16x32_bf16 v[86:89], v[20:23], v[200:203], v[164:167]
	s_nop 1
	v_ashrrev_i32_e32 v70, 31, v24
	v_bitop3_b32 v24, v70, v24, s57 bitop3:0x36
	v_and_or_b32 v83, v24, s58, v134
	v_ashrrev_i32_e32 v24, 31, v25
	v_mfma_f32_16x16x32_bf16 v[66:69], v[16:19], v[168:171], v[66:69]
	v_bitop3_b32 v16, v24, v25, s57 bitop3:0x36
	v_and_or_b32 v84, v16, s58, v135
	v_ashrrev_i32_e32 v16, 31, v26
	v_bitop3_b32 v16, v16, v26, s57 bitop3:0x36
	v_and_or_b32 v85, v16, s58, v136
	s_waitcnt vmcnt(0)
	v_mfma_f32_16x16x32_bf16 v[16:19], v[244:247], v[216:219], v[86:89]
	v_ashrrev_i32_e32 v24, 31, v27
	v_bitop3_b32 v24, v24, v27, s57 bitop3:0x36
	v_mfma_f32_16x16x32_bf16 v[0:3], v[232:235], v[200:203], v[0:3]
	v_and_or_b32 v86, v24, s58, v137
	s_nop 3
	v_ashrrev_i32_e32 v24, 31, v16
	v_bitop3_b32 v16, v24, v16, s57 bitop3:0x36
	v_and_or_b32 v87, v16, s58, v138
	v_ashrrev_i32_e32 v16, 31, v17
	v_bitop3_b32 v16, v16, v17, s57 bitop3:0x36
	v_and_or_b32 v88, v16, s58, v139
	v_ashrrev_i32_e32 v16, 31, v18
	v_mfma_f32_16x16x32_bf16 v[0:3], v[28:31], v[216:219], v[0:3]
	v_mfma_f32_16x16x32_bf16 v[70:73], v[212:215], v[168:171], v[74:77]
	v_mfma_f32_16x16x32_bf16 v[74:77], v[220:223], v[168:171], v[78:81]
	v_mfma_f32_16x16x32_bf16 v[78:81], v[20:23], v[168:171], v[36:39]
	v_mfma_f32_16x16x32_bf16 v[36:39], v[232:235], v[168:171], v[4:7]
	s_nop 2
	v_bitop3_b32 v4, v16, v18, s57 bitop3:0x36
	v_and_or_b32 v89, v4, s58, v140
	v_ashrrev_i32_e32 v4, 31, v19
	v_bitop3_b32 v4, v4, v19, s57 bitop3:0x36
	v_and_or_b32 v162, v4, s58, v141
	v_ashrrev_i32_e32 v4, 31, v0
	v_bitop3_b32 v0, v4, v0, s57 bitop3:0x36
	v_mfma_f32_16x16x32_bf16 v[44:47], v[224:227], v[168:171], v[44:47]
	v_and_or_b32 v163, v0, s58, v142
	v_ashrrev_i32_e32 v0, 31, v1
	v_bitop3_b32 v0, v0, v1, s57 bitop3:0x36
	v_and_or_b32 v164, v0, s58, v143
	v_ashrrev_i32_e32 v0, 31, v2
	v_mfma_f32_16x16x32_bf16 v[8:11], v[172:175], v[168:171], v[8:11]
	v_bitop3_b32 v0, v0, v2, s57 bitop3:0x36
; __device__ __forceinline__ f32x4 mfma16(bf16x8 a, bf16x8 b, f32x4 c) { return __builtin_amdgcn_mfma_f32_16x16x32_bf16(a, b, c, 0, 0, 0); }
; __device__ void phase_peer(const Params& P, unsigned char* smem) {
;     ...
;                         for (int tn = 0; tn < 8; ++tn) acc[th][tn] = mfma16(kf[tn], qf[th], acc[th][tn]);
;     ...
;                     for (int k = 2; k <= 32; k <<= 1)
; #pragma unroll
;                         for (int j = k >> 1; j >= 1; j >>= 1)
; #pragma unroll
;                             for (int i = 0; i < 32; ++i) {
;                                 const int l = i ^ j;
;                                 if (l > i) {
;                                     const unsigned hi_ = max(S32[i], S32[l]), lo_ = min(S32[i], S32[l]);
;                                     if ((i & k) == 0) { S32[i] = hi_; S32[l] = lo_; } else { S32[i] = lo_; S32[l] = hi_; }
;                                 }
;                             }
	v_mfma_f32_16x16x32_bf16 v[12:15], v[180:183], v[168:171], v[12:15]
	v_mfma_f32_16x16x32_bf16 v[16:19], v[228:231], v[32:35], v[44:47]
	s_nop 2
	v_and_or_b32 v44, v0, s58, v145
	v_ashrrev_i32_e32 v0, 31, v3
	v_bitop3_b32 v0, v0, v3, s57 bitop3:0x36
	v_and_or_b32 v45, v0, s58, v148
	v_mfma_f32_16x16x32_bf16 v[24:27], v[208:211], v[32:35], v[8:11]
	v_max_u32_e32 v46, v48, v176
	v_min_u32_e32 v47, v48, v176
	v_max_u32_e32 v48, v177, v178
	v_mfma_f32_16x16x32_bf16 v[20:23], v[204:207], v[32:35], v[12:15]
	v_mfma_f32_16x16x32_bf16 v[12:15], v[236:239], v[32:35], v[66:69]
	v_mfma_f32_16x16x32_bf16 v[8:11], v[98:101], v[32:35], v[70:73]
	s_nop 1
	v_min_u32_e32 v66, v177, v178
	v_max_u32_e32 v67, v179, v90
	v_min_u32_e32 v68, v179, v90
	v_mfma_f32_16x16x32_bf16 v[4:7], v[192:195], v[32:35], v[74:77]
	v_max_u32_e32 v69, v91, v92
	v_min_u32_e32 v70, v91, v92
	v_max_u32_e32 v71, v93, v94
	v_mfma_f32_16x16x32_bf16 v[0:3], v[244:247], v[32:35], v[78:81]
	v_min_u32_e32 v72, v93, v94
	v_max_u32_e32 v73, v95, v96
	v_min_u32_e32 v74, v95, v96
	v_max_u32_e32 v75, v97, v102
	v_min_u32_e32 v76, v97, v102
	v_max_u32_e32 v77, v103, v104
	v_min_u32_e32 v78, v103, v104
	v_max_u32_e32 v79, v105, v160
	v_min_u32_e32 v80, v105, v160
	v_max_u32_e32 v81, v161, v82
	v_min_u32_e32 v82, v161, v82
	v_max_u32_e32 v90, v83, v84
	v_min_u32_e32 v83, v83, v84
	v_max_u32_e32 v84, v85, v86
	v_min_u32_e32 v85, v85, v86
	v_max_u32_e32 v86, v87, v88
	v_min_u32_e32 v87, v87, v88
	v_max_u32_e32 v88, v89, v162
	v_min_u32_e32 v89, v89, v162
	v_max_u32_e32 v91, v163, v164
	v_min_u32_e32 v92, v163, v164
	v_max_u32_e32 v93, v44, v45
	v_min_u32_e32 v44, v44, v45
	v_max_u32_e32 v45, v46, v66
	v_min_u32_e32 v46, v46, v66
	v_max_u32_e32 v66, v47, v48
	v_min_u32_e32 v47, v47, v48
	v_max_u32_e32 v48, v67, v70
	v_min_u32_e32 v67, v67, v70
	v_max_u32_e32 v70, v68, v69
	v_min_u32_e32 v68, v68, v69
	v_max_u32_e32 v69, v71, v74
	v_min_u32_e32 v71, v71, v74
	v_max_u32_e32 v74, v72, v73
	v_min_u32_e32 v72, v72, v73
	v_max_u32_e32 v73, v75, v78
	v_min_u32_e32 v75, v75, v78
	v_max_u32_e32 v78, v76, v77
	v_min_u32_e32 v76, v76, v77
	v_max_u32_e32 v77, v79, v82
	v_min_u32_e32 v79, v79, v82
	v_max_u32_e32 v82, v80, v81
	v_min_u32_e32 v80, v80, v81
	v_max_u32_e32 v81, v90, v85
	v_min_u32_e32 v85, v90, v85
	v_max_u32_e32 v90, v83, v84
	v_min_u32_e32 v83, v83, v84
	v_max_u32_e32 v84, v86, v89
	v_min_u32_e32 v86, v86, v89
	v_max_u32_e32 v89, v87, v88
	v_min_u32_e32 v87, v87, v88
	v_max_u32_e32 v88, v91, v44
	v_min_u32_e32 v44, v91, v44
	v_max_u32_e32 v91, v92, v93
	v_min_u32_e32 v92, v92, v93
	v_max_u32_e32 v93, v45, v66
	v_min_u32_e32 v45, v45, v66
	v_max_u32_e32 v66, v46, v47
	v_min_u32_e32 v46, v46, v47
	v_max_u32_e32 v47, v67, v68
	v_min_u32_e32 v67, v67, v68
	v_max_u32_e32 v68, v48, v70
	v_min_u32_e32 v48, v48, v70
	v_max_u32_e32 v70, v69, v74
	v_min_u32_e32 v69, v69, v74
	v_max_u32_e32 v74, v71, v72
	v_min_u32_e32 v71, v71, v72
	v_max_u32_e32 v72, v75, v76
	v_min_u32_e32 v75, v75, v76
	v_max_u32_e32 v76, v73, v78
	v_min_u32_e32 v73, v73, v78
	v_max_u32_e32 v78, v77, v82
	v_min_u32_e32 v77, v77, v82
	v_max_u32_e32 v82, v79, v80
	v_min_u32_e32 v79, v79, v80
	v_max_u32_e32 v80, v85, v83
	v_min_u32_e32 v83, v85, v83
	v_max_u32_e32 v85, v81, v90
	v_min_u32_e32 v81, v81, v90
	v_max_u32_e32 v90, v84, v89
	v_min_u32_e32 v84, v84, v89
	v_max_u32_e32 v89, v86, v87
	v_min_u32_e32 v86, v86, v87
	v_max_u32_e32 v87, v44, v92
	v_min_u32_e32 v44, v44, v92
	v_max_u32_e32 v92, v88, v91
	v_min_u32_e32 v88, v88, v91
	v_max_u32_e32 v91, v93, v67
	v_min_u32_e32 v67, v93, v67
	v_max_u32_e32 v93, v45, v47
	v_min_u32_e32 v45, v45, v47
	v_max_u32_e32 v47, v66, v48
	v_min_u32_e32 v48, v66, v48
	v_max_u32_e32 v66, v46, v68
	v_min_u32_e32 v46, v46, v68
	v_max_u32_e32 v68, v70, v75
	v_min_u32_e32 v70, v70, v75
	v_max_u32_e32 v75, v69, v72
	v_min_u32_e32 v69, v69, v72
	v_max_u32_e32 v72, v74, v73
	v_min_u32_e32 v73, v74, v73
	v_max_u32_e32 v74, v71, v76
	v_min_u32_e32 v71, v71, v76
	v_max_u32_e32 v76, v78, v83
	v_min_u32_e32 v78, v78, v83
	v_max_u32_e32 v83, v77, v80
	v_min_u32_e32 v77, v77, v80
	v_max_u32_e32 v80, v82, v81
	v_min_u32_e32 v81, v82, v81
	v_max_u32_e32 v82, v79, v85
	v_min_u32_e32 v79, v79, v85
	v_max_u32_e32 v85, v90, v44
	v_min_u32_e32 v44, v90, v44
	v_max_u32_e32 v90, v84, v87
	v_min_u32_e32 v84, v84, v87
	v_max_u32_e32 v87, v89, v88
	v_min_u32_e32 v88, v89, v88
	v_max_u32_e32 v89, v86, v92
	v_min_u32_e32 v86, v86, v92
	v_max_u32_e32 v92, v91, v47
	v_min_u32_e32 v47, v91, v47
	v_max_u32_e32 v91, v93, v66
	v_min_u32_e32 v66, v93, v66
	v_max_u32_e32 v93, v67, v48
	v_min_u32_e32 v48, v67, v48
	v_max_u32_e32 v67, v45, v46
	v_min_u32_e32 v45, v45, v46
	v_max_u32_e32 v46, v70, v73
	v_min_u32_e32 v70, v70, v73
	v_max_u32_e32 v73, v69, v71
	v_min_u32_e32 v69, v69, v71
	v_max_u32_e32 v71, v68, v72
	v_min_u32_e32 v68, v68, v72
	v_max_u32_e32 v72, v75, v74
	v_min_u32_e32 v74, v75, v74
	v_max_u32_e32 v75, v76, v80
	v_min_u32_e32 v76, v76, v80
	v_max_u32_e32 v80, v83, v82
	v_min_u32_e32 v82, v83, v82
	v_max_u32_e32 v83, v78, v81
	v_min_u32_e32 v78, v78, v81
	v_max_u32_e32 v81, v77, v79
	v_min_u32_e32 v77, v77, v79
	v_max_u32_e32 v79, v44, v88
	v_min_u32_e32 v44, v44, v88
	v_max_u32_e32 v88, v84, v86
	v_min_u32_e32 v84, v84, v86
	v_max_u32_e32 v86, v85, v87
	v_min_u32_e32 v85, v85, v87
	v_max_u32_e32 v87, v90, v89
	v_min_u32_e32 v89, v90, v89
	v_max_u32_e32 v90, v92, v91
	v_min_u32_e32 v91, v92, v91
	v_max_u32_e32 v92, v47, v66
	v_min_u32_e32 v47, v47, v66
	v_max_u32_e32 v66, v93, v67
	v_min_u32_e32 v67, v93, v67
	v_max_u32_e32 v93, v48, v45
	v_min_u32_e32 v45, v48, v45
	v_max_u32_e32 v48, v70, v69
	v_min_u32_e32 v69, v70, v69
; __device__ void phase_peer(const Params& P, unsigned char* smem) {
;     ...
;                     for (int k = 2; k <= 32; k <<= 1)
; #pragma unroll
;                         for (int j = k >> 1; j >= 1; j >>= 1)
; #pragma unroll
;                             for (int i = 0; i < 32; ++i) {
;                                 const int l = i ^ j;
;                                 if (l > i) {
;                                     const unsigned hi_ = max(S32[i], S32[l]), lo_ = min(S32[i], S32[l]);
;                                     if ((i & k) == 0) { S32[i] = hi_; S32[l] = lo_; } else { S32[i] = lo_; S32[l] = hi_; }
;                                 }
;                             }
;                     unsigned L[16];
; #pragma unroll
;                     for (int q = 0; q < 16; ++q) L[q] = S32[q];
; #pragma unroll
;                     for (int rnd = 0; rnd < 2; ++rnd) {
;                         unsigned R[16];
; #pragma unroll
;                         for (int q = 0; q < 16; ++q) R[q] = (unsigned)__shfl_xor((int)L[q], 16 << rnd);
	v_max_u32_e32 v70, v46, v73
	v_min_u32_e32 v46, v46, v73
	v_max_u32_e32 v73, v68, v74
	v_min_u32_e32 v68, v68, v74
	v_max_u32_e32 v74, v71, v72
	v_min_u32_e32 v71, v71, v72
	v_max_u32_e32 v72, v75, v80
	v_min_u32_e32 v75, v75, v80
	v_max_u32_e32 v80, v76, v82
	v_min_u32_e32 v76, v76, v82
	v_max_u32_e32 v82, v83, v81
	v_min_u32_e32 v81, v83, v81
	v_max_u32_e32 v83, v78, v77
	v_min_u32_e32 v77, v78, v77
	v_max_u32_e32 v78, v44, v84
	v_min_u32_e32 v44, v44, v84
	v_max_u32_e32 v84, v79, v88
	v_min_u32_e32 v79, v79, v88
	v_max_u32_e32 v88, v85, v89
	v_min_u32_e32 v85, v85, v89
	v_max_u32_e32 v89, v86, v87
	v_min_u32_e32 v86, v86, v87
	v_max_u32_e32 v87, v90, v69
	v_min_u32_e32 v69, v90, v69
	v_max_u32_e32 v90, v91, v48
	v_min_u32_e32 v48, v91, v48
	v_max_u32_e32 v91, v92, v46
	v_min_u32_e32 v46, v92, v46
	v_max_u32_e32 v92, v47, v70
	v_min_u32_e32 v47, v47, v70
	v_max_u32_e32 v70, v66, v68
	v_min_u32_e32 v66, v66, v68
	v_max_u32_e32 v68, v67, v73
	v_min_u32_e32 v67, v67, v73
	v_max_u32_e32 v73, v93, v71
	v_min_u32_e32 v71, v93, v71
	v_max_u32_e32 v93, v45, v74
	v_min_u32_e32 v45, v45, v74
	v_max_u32_e32 v74, v72, v44
	v_min_u32_e32 v44, v72, v44
	v_max_u32_e32 v72, v75, v78
	v_min_u32_e32 v75, v75, v78
	v_max_u32_e32 v78, v80, v79
	v_min_u32_e32 v79, v80, v79
	v_max_u32_e32 v80, v76, v84
	v_min_u32_e32 v76, v76, v84
	v_max_u32_e32 v84, v82, v85
	v_min_u32_e32 v82, v82, v85
	v_max_u32_e32 v85, v81, v88
	v_min_u32_e32 v81, v81, v88
	v_max_u32_e32 v88, v83, v86
	v_min_u32_e32 v83, v83, v86
	v_max_u32_e32 v86, v77, v89
	v_min_u32_e32 v77, v77, v89
	v_max_u32_e32 v89, v87, v70
	v_min_u32_e32 v70, v87, v70
	v_max_u32_e32 v87, v90, v68
	v_min_u32_e32 v68, v90, v68
	v_max_u32_e32 v90, v91, v73
	v_min_u32_e32 v73, v91, v73
	v_max_u32_e32 v91, v92, v93
	v_min_u32_e32 v92, v92, v93
	v_max_u32_e32 v93, v69, v66
	v_min_u32_e32 v66, v69, v66
	v_max_u32_e32 v69, v48, v67
	v_min_u32_e32 v48, v48, v67
	v_max_u32_e32 v67, v46, v71
	v_min_u32_e32 v46, v46, v71
	v_max_u32_e32 v71, v47, v45
	v_min_u32_e32 v45, v47, v45
	v_max_u32_e32 v47, v44, v82
	v_min_u32_e32 v44, v44, v82
	v_max_u32_e32 v82, v75, v81
	v_min_u32_e32 v75, v75, v81
	v_max_u32_e32 v81, v79, v83
	v_min_u32_e32 v79, v79, v83
	v_max_u32_e32 v83, v76, v77
	v_min_u32_e32 v76, v76, v77
	v_max_u32_e32 v77, v74, v84
	v_min_u32_e32 v74, v74, v84
	v_max_u32_e32 v84, v72, v85
	v_min_u32_e32 v72, v72, v85
	v_max_u32_e32 v85, v78, v88
	v_min_u32_e32 v78, v78, v88
	v_max_u32_e32 v88, v80, v86
	v_min_u32_e32 v80, v80, v86
	v_max_u32_e32 v86, v89, v90
	v_min_u32_e32 v89, v89, v90
	v_max_u32_e32 v90, v87, v91
	v_min_u32_e32 v87, v87, v91
	v_max_u32_e32 v91, v70, v73
	v_min_u32_e32 v70, v70, v73
	v_max_u32_e32 v73, v68, v92
	v_min_u32_e32 v68, v68, v92
	v_max_u32_e32 v92, v93, v67
	v_min_u32_e32 v67, v93, v67
	v_max_u32_e32 v93, v69, v71
	v_min_u32_e32 v69, v69, v71
	v_max_u32_e32 v71, v66, v46
	v_min_u32_e32 v46, v66, v46
	v_max_u32_e32 v66, v48, v45
	v_min_u32_e32 v45, v48, v45
	v_max_u32_e32 v48, v44, v79
	v_min_u32_e32 v44, v44, v79
	v_max_u32_e32 v79, v75, v76
	v_min_u32_e32 v75, v75, v76
	v_max_u32_e32 v76, v47, v81
	v_min_u32_e32 v47, v47, v81
	v_max_u32_e32 v81, v82, v83
	v_min_u32_e32 v82, v82, v83
	v_max_u32_e32 v83, v74, v78
	v_min_u32_e32 v74, v74, v78
	v_max_u32_e32 v78, v72, v80
	v_min_u32_e32 v72, v72, v80
	v_max_u32_e32 v80, v77, v85
	v_min_u32_e32 v77, v77, v85
	v_max_u32_e32 v85, v84, v88
	v_min_u32_e32 v84, v84, v88
	v_min_u32_e32 v88, v86, v90
	v_min_u32_e32 v94, v89, v87
	v_min_u32_e32 v95, v91, v73
	v_min_u32_e32 v96, v70, v68
	v_min_u32_e32 v97, v92, v93
	v_min_u32_e32 v98, v67, v69
	v_min_u32_e32 v99, v71, v66
	v_min_u32_e32 v100, v46, v45
	v_min_u32_e32 v101, v44, v75
	v_min_u32_e32 v102, v48, v79
	v_min_u32_e32 v103, v47, v82
	v_min_u32_e32 v104, v76, v81
	v_min_u32_e32 v105, v74, v72
	v_min_u32_e32 v160, v83, v78
	v_min_u32_e32 v161, v77, v84
	v_min_u32_e32 v162, v80, v85
	v_max3_u32 v86, v86, v90, v101
	v_max3_u32 v44, v88, v44, v75
	v_max3_u32 v75, v89, v87, v102
	v_max3_u32 v48, v94, v48, v79
	v_max3_u32 v73, v91, v73, v103
	v_max3_u32 v47, v95, v47, v82
	v_max3_u32 v68, v70, v68, v104
	v_max3_u32 v70, v96, v76, v81
	v_max3_u32 v76, v92, v93, v105
	v_max3_u32 v72, v97, v74, v72
	v_max3_u32 v67, v67, v69, v160
	v_max3_u32 v69, v98, v83, v78
	v_max3_u32 v66, v71, v66, v161
	v_max3_u32 v71, v99, v77, v84
	v_max3_u32 v45, v46, v45, v162
	v_max3_u32 v46, v100, v80, v85
	v_max_u32_e32 v74, v86, v76
	v_min_u32_e32 v76, v86, v76
	v_max_u32_e32 v77, v44, v72
	v_min_u32_e32 v44, v44, v72
	v_max_u32_e32 v72, v75, v67
	v_min_u32_e32 v67, v75, v67
	v_max_u32_e32 v75, v48, v69
	v_min_u32_e32 v48, v48, v69
	v_max_u32_e32 v69, v73, v66
	v_min_u32_e32 v66, v73, v66
	v_max_u32_e32 v73, v47, v71
	v_min_u32_e32 v47, v47, v71
	v_max_u32_e32 v71, v68, v45
	v_min_u32_e32 v45, v68, v45
	v_max_u32_e32 v68, v70, v46
	v_min_u32_e32 v46, v70, v46
	v_max_u32_e32 v70, v74, v69
	v_min_u32_e32 v69, v74, v69
	v_max_u32_e32 v74, v77, v73
	v_min_u32_e32 v73, v77, v73
	v_max_u32_e32 v77, v72, v71
	v_min_u32_e32 v71, v72, v71
	v_max_u32_e32 v72, v75, v68
	v_min_u32_e32 v68, v75, v68
	v_max_u32_e32 v75, v76, v66
	v_min_u32_e32 v66, v76, v66
	v_max_u32_e32 v76, v44, v47
	v_min_u32_e32 v44, v44, v47
	v_max_u32_e32 v47, v67, v45
	v_min_u32_e32 v45, v67, v45
	v_max_u32_e32 v67, v48, v46
	v_min_u32_e32 v46, v48, v46
	v_max_u32_e32 v48, v70, v77
	v_min_u32_e32 v70, v70, v77
	v_max_u32_e32 v77, v74, v72
	v_min_u32_e32 v72, v74, v72
	v_max_u32_e32 v74, v69, v71
	v_min_u32_e32 v69, v69, v71
	v_max_u32_e32 v71, v73, v68
	v_min_u32_e32 v68, v73, v68
	v_max_u32_e32 v73, v75, v47
	v_min_u32_e32 v47, v75, v47
	v_max_u32_e32 v75, v76, v67
	v_min_u32_e32 v67, v76, v67
	v_max_u32_e32 v76, v66, v45
	v_min_u32_e32 v45, v66, v45
	v_max_u32_e32 v66, v44, v46
	v_min_u32_e32 v44, v44, v46
	v_max_u32_e32 v46, v48, v77
	v_min_u32_e32 v48, v48, v77
	v_max_u32_e32 v77, v70, v72
	v_min_u32_e32 v70, v70, v72
	v_max_u32_e32 v72, v74, v71
	v_min_u32_e32 v71, v74, v71
	v_max_u32_e32 v74, v69, v68
	v_min_u32_e32 v68, v69, v68
	v_max_u32_e32 v69, v73, v75
	v_min_u32_e32 v73, v73, v75
	v_max_u32_e32 v75, v47, v67
	v_min_u32_e32 v47, v47, v67
	v_max_u32_e32 v67, v76, v66
	v_min_u32_e32 v66, v76, v66
	v_max_u32_e32 v76, v45, v44
	v_min_u32_e32 v44, v45, v44
	ds_bpermute_b32 v45, v42, v46
	ds_bpermute_b32 v78, v42, v48
	ds_bpermute_b32 v79, v42, v77
	ds_bpermute_b32 v80, v42, v70
	ds_bpermute_b32 v81, v42, v72
	ds_bpermute_b32 v82, v42, v71
	ds_bpermute_b32 v83, v42, v74
	ds_bpermute_b32 v84, v42, v68
	ds_bpermute_b32 v85, v42, v69
	ds_bpermute_b32 v86, v42, v73
	ds_bpermute_b32 v87, v42, v75
	ds_bpermute_b32 v88, v42, v76
	ds_bpermute_b32 v89, v42, v66
	ds_bpermute_b32 v90, v42, v67
	ds_bpermute_b32 v91, v42, v47
	ds_bpermute_b32 v92, v42, v44
	s_waitcnt lgkmcnt(4)
; __device__ void phase_peer(const Params& P, unsigned char* smem) {
;     ...
;                         for (int q = 0; q < 16; ++q) R[q] = (unsigned)__shfl_xor((int)L[q], 16 << rnd);
; #pragma unroll
;                         for (int q = 0; q < 16; ++q) L[q] = max(L[q], R[15 - q]);
; #pragma unroll
;                         for (int d = 8; d >= 1; d >>= 1)
; #pragma unroll
;                             for (int q = 0; q < 16; ++q)
;                                 if ((q & d) == 0) { const unsigned hi_ = max(L[q], L[q + d]), lo_ = min(L[q], L[q + d]); L[q] = hi_; L[q + d] = lo_; }
;                     }
;                     if (l4 == 0) {
	v_max_u32_e32 v48, v48, v88
	s_waitcnt lgkmcnt(3)
	v_max_u32_e32 v77, v77, v89
	s_waitcnt lgkmcnt(2)
	v_max_u32_e32 v70, v70, v90
	s_waitcnt lgkmcnt(1)
	v_max_u32_e32 v72, v72, v91
	v_max_u32_e32 v71, v71, v87
	v_max_u32_e32 v74, v74, v86
	v_max_u32_e32 v68, v68, v85
	v_max_u32_e32 v73, v73, v83
	v_max_u32_e32 v75, v75, v82
	v_max_u32_e32 v47, v47, v81
	v_max_u32_e32 v67, v67, v80
	v_max_u32_e32 v66, v66, v79
	v_max_u32_e32 v76, v76, v78
	v_max_u32_e32 v44, v44, v45
	v_max_u32_e32 v45, v69, v84
	s_waitcnt lgkmcnt(0)
	v_max_u32_e32 v46, v46, v92
	v_max_u32_e32 v69, v46, v45
	v_min_u32_e32 v45, v46, v45
	v_max_u32_e32 v46, v48, v73
	v_min_u32_e32 v48, v48, v73
	v_max_u32_e32 v73, v77, v75
	v_min_u32_e32 v75, v77, v75
	v_max_u32_e32 v77, v70, v47
	v_min_u32_e32 v47, v70, v47
	v_max_u32_e32 v70, v72, v67
	v_min_u32_e32 v67, v72, v67
	v_max_u32_e32 v72, v71, v66
	v_min_u32_e32 v66, v71, v66
	v_max_u32_e32 v71, v74, v76
	v_min_u32_e32 v74, v74, v76
	v_max_u32_e32 v76, v68, v44
	v_min_u32_e32 v44, v68, v44
	v_max_u32_e32 v68, v69, v70
	v_min_u32_e32 v69, v69, v70
	v_max_u32_e32 v70, v46, v72
	v_min_u32_e32 v46, v46, v72
	v_max_u32_e32 v72, v73, v71
	v_min_u32_e32 v71, v73, v71
	v_max_u32_e32 v73, v77, v76
	v_min_u32_e32 v76, v77, v76
	v_max_u32_e32 v77, v45, v67
	v_min_u32_e32 v45, v45, v67
	v_max_u32_e32 v67, v48, v66
	v_min_u32_e32 v48, v48, v66
	v_max_u32_e32 v66, v75, v74
	v_min_u32_e32 v74, v75, v74
	v_max_u32_e32 v75, v47, v44
	v_min_u32_e32 v44, v47, v44
	v_max_u32_e32 v47, v68, v72
	v_min_u32_e32 v68, v68, v72
	v_max_u32_e32 v72, v70, v73
	v_min_u32_e32 v73, v70, v73
	v_max_u32_e32 v78, v69, v71
	v_min_u32_e32 v69, v69, v71
	v_max_u32_e32 v71, v46, v76
	v_min_u32_e32 v79, v46, v76
	v_max_u32_e32 v80, v77, v66
	v_min_u32_e32 v66, v77, v66
	v_max_u32_e32 v77, v67, v75
	v_min_u32_e32 v67, v67, v75
	v_max_u32_e32 v81, v45, v74
	v_min_u32_e32 v74, v45, v74
	v_max_u32_e32 v84, v48, v44
	v_min_u32_e32 v85, v48, v44
	v_max_u32_e32 v75, v47, v72
	v_min_u32_e32 v46, v47, v72
	v_max_u32_e32 v70, v68, v73
	v_min_u32_e32 v44, v68, v73
	v_max_u32_e32 v76, v78, v71
	v_min_u32_e32 v47, v78, v71
	v_max_u32_e32 v71, v69, v79
	v_min_u32_e32 v45, v69, v79
	v_max_u32_e32 v82, v80, v77
	v_min_u32_e32 v68, v80, v77
	v_max_u32_e32 v77, v66, v67
	v_min_u32_e32 v48, v66, v67
	v_max_u32_e32 v83, v81, v84
	v_min_u32_e32 v69, v81, v84
	v_max_u32_e32 v78, v74, v85
	v_min_u32_e32 v66, v74, v85
	ds_bpermute_b32 v67, v43, v75
	ds_bpermute_b32 v79, v43, v46
	ds_bpermute_b32 v73, v43, v70
	ds_bpermute_b32 v86, v43, v44
	ds_bpermute_b32 v72, v43, v76
	ds_bpermute_b32 v85, v43, v47
	ds_bpermute_b32 v80, v43, v71
	ds_bpermute_b32 v89, v43, v45
	ds_bpermute_b32 v74, v43, v82
	ds_bpermute_b32 v87, v43, v68
	ds_bpermute_b32 v84, v43, v77
	ds_bpermute_b32 v91, v43, v48
	ds_bpermute_b32 v81, v43, v83
	ds_bpermute_b32 v90, v43, v69
	ds_bpermute_b32 v88, v43, v78
	ds_bpermute_b32 v92, v43, v66
	v_mfma_f32_16x16x32_bf16 v[28:31], v[28:31], v[32:35], v[36:39]
	s_and_saveexec_b64 s[0:1], s[4:5]
	s_cbranch_execz .LBB0_963
; __device__ void phase_peer(const Params& P, unsigned char* smem) {
;     ...
;                         for (int q = 0; q < 16; ++q) L[q] = max(L[q], R[15 - q]);
; #pragma unroll
;                         for (int d = 8; d >= 1; d >>= 1)
; #pragma unroll
;                             for (int q = 0; q < 16; ++q)
;                                 if ((q & d) == 0) { const unsigned hi_ = max(L[q], L[q + d]), lo_ = min(L[q], L[q + d]); L[q] = hi_; L[q + d] = lo_; }
;                     }
;                     if (l4 == 0) {
;                         const int tok = th * 16 + l15;
;                         float* svp = sv + ((tok * 8 + h) * 2 + (p & 1)) * 16; unsigned char* sip = si + ((tok * 8 + h) * 2 + (p & 1)) * 16;
; #pragma unroll
;                         for (int q = 0; q < 16; ++q) { const unsigned u_ = L[q] & ~127u; svp[q] = __uint_as_float((u_ & 0x80000000u) ? (u_ ^ 0x80000000u) : ~u_); sip[q] = (unsigned char)(L[q] & 127u); }
	s_waitcnt lgkmcnt(0)
	v_max_u32_e32 v32, v75, v92
	v_max_u32_e32 v33, v82, v89
	v_max_u32_e32 v35, v76, v91
	v_max_u32_e32 v36, v83, v86
	v_max_u32_e32 v39, v70, v90
	v_max_u32_e32 v70, v77, v85
	v_max_u32_e32 v71, v71, v87
	v_max_u32_e32 v76, v78, v79
	v_max_u32_e32 v46, v46, v88
	v_max_u32_e32 v68, v68, v80
	v_max_u32_e32 v47, v47, v84
	v_max_u32_e32 v69, v69, v73
	v_max_u32_e32 v44, v44, v81
	v_max_u32_e32 v48, v48, v72
	v_max_u32_e32 v45, v45, v74
	v_max_u32_e32 v66, v66, v67
	v_min_u32_e32 v34, v32, v33
	v_min_u32_e32 v37, v35, v36
	v_min_u32_e32 v75, v39, v70
	v_min_u32_e32 v77, v71, v76
	v_min_u32_e32 v80, v46, v68
	v_min_u32_e32 v73, v47, v69
	v_min_u32_e32 v72, v44, v48
	v_min_u32_e32 v67, v45, v66
	v_min_u32_e32 v38, v34, v37
	v_min_u32_e32 v78, v75, v77
	v_min_u32_e32 v82, v80, v73
	v_min_u32_e32 v74, v72, v67
	v_min_u32_e32 v79, v38, v78
	v_min_u32_e32 v81, v82, v74
	v_max_u32_e32 v38, v38, v78
	v_max_u32_e32 v74, v82, v74
	v_max_u32_e32 v34, v34, v37
	v_max_u32_e32 v37, v75, v77
	v_max_u32_e32 v73, v80, v73
	v_max_u32_e32 v67, v72, v67
	v_min_u32_e32 v78, v38, v74
	v_max_u32_e32 v38, v38, v74
	v_min_u32_e32 v74, v34, v37
	v_max_u32_e32 v34, v34, v37
	v_max_u32_e32 v37, v73, v67
	v_max_u32_e32 v32, v32, v33
	v_max_u32_e32 v33, v35, v36
	v_max_u32_e32 v35, v39, v70
	v_max_u32_e32 v36, v71, v76
	v_max_u32_e32 v46, v46, v68
	v_max_u32_e32 v47, v47, v69
	v_max_u32_e32 v44, v44, v48
	v_max_u32_e32 v45, v45, v66
	v_min_u32_e32 v72, v73, v67
	v_min_u32_e32 v67, v34, v37
	v_max_u32_e32 v37, v34, v37
	v_min_u32_e32 v34, v32, v33
	v_min_u32_e32 v39, v35, v36
	v_min_u32_e32 v68, v46, v47
	v_min_u32_e32 v48, v44, v45
	v_min_u32_e32 v70, v34, v39
	v_max_u32_e32 v34, v34, v39
	v_max_u32_e32 v39, v68, v48
	v_max_u32_e32 v32, v32, v33
	v_max_u32_e32 v33, v35, v36
	v_max_u32_e32 v35, v46, v47
	v_max_u32_e32 v36, v44, v45
	v_min_u32_e32 v66, v68, v48
	v_min_u32_e32 v48, v34, v39
	v_max_u32_e32 v39, v34, v39
	v_min_u32_e32 v34, v32, v33
	v_min_u32_e32 v44, v35, v36
	v_max_u32_e32 v32, v32, v33
	v_max_u32_e32 v33, v35, v36
	v_min_u32_e32 v45, v34, v44
	v_max_u32_e32 v44, v34, v44
	v_min_u32_e32 v34, v32, v33
	v_max_u32_e32 v36, v32, v33
	v_or_b32_e32 v32, s18, v149
	v_lshl_add_u32 v33, v32, 2, 0
	v_cmp_lt_i32_e32 vcc, -1, v34
	v_add_u32_e32 v46, 0x18000, v33
	v_add_u32_e32 v32, 0, v32
	v_cndmask_b32_e64 v33, v157, -1, vcc
	v_cmp_lt_i32_e32 vcc, -1, v36
	v_add_u32_e32 v47, 0x20000, v32
	v_and_b32_e32 v32, 0xffffff80, v34
	v_and_b32_e32 v35, 0xffffff80, v36
	v_cndmask_b32_e64 v68, v157, -1, vcc
	v_cmp_lt_i32_e32 vcc, -1, v45
	v_xor_b32_e32 v33, v33, v32
	v_xor_b32_e32 v32, v68, v35
	v_cndmask_b32_e64 v35, v157, -1, vcc
	v_cmp_lt_i32_e32 vcc, -1, v44
	v_min_u32_e32 v69, v70, v66
	v_max_u32_e32 v66, v70, v66
	v_and_b32_sdwa v68, v34, s59 dst_sel:BYTE_1 dst_unused:UNUSED_PAD src0_sel:DWORD src1_sel:DWORD
	v_and_b32_e32 v34, 0xffffff80, v45
	v_and_b32_e32 v70, 0xffffff80, v44
	v_cndmask_b32_e64 v71, v157, -1, vcc
	v_xor_b32_e32 v35, v35, v34
	v_xor_b32_e32 v34, v71, v70
	v_cmp_lt_i32_e32 vcc, -1, v48
	ds_write_b128 v46, v[32:35]
	v_and_b32_e32 v32, 0xffffff80, v48
	v_cndmask_b32_e64 v33, v157, -1, vcc
	v_cmp_lt_i32_e32 vcc, -1, v39
	v_and_b32_e32 v34, 0xffffff80, v39
	v_xor_b32_e32 v33, v33, v32
	v_cndmask_b32_e64 v35, v157, -1, vcc
	v_cmp_lt_i32_e32 vcc, -1, v69
	v_xor_b32_e32 v32, v35, v34
	v_and_b32_e32 v34, 0xffffff80, v69
	v_cndmask_b32_e64 v35, v157, -1, vcc
	v_cmp_lt_i32_e32 vcc, -1, v66
	v_and_b32_e32 v70, 0xffffff80, v66
	v_xor_b32_e32 v35, v35, v34
	v_cndmask_b32_e64 v71, v157, -1, vcc
	v_xor_b32_e32 v34, v71, v70
	v_cmp_lt_i32_e32 vcc, -1, v67
	v_min_u32_e32 v75, v74, v72
	ds_write_b128 v46, v[32:35] offset:16
	v_cndmask_b32_e64 v33, v157, -1, vcc
	v_cmp_lt_i32_e32 vcc, -1, v37
	v_max_u32_e32 v72, v74, v72
	v_and_b32_e32 v32, 0xffffff80, v67
	v_and_b32_e32 v34, 0xffffff80, v37
	v_cndmask_b32_e64 v35, v157, -1, vcc
	v_cmp_lt_i32_e32 vcc, -1, v75
	v_xor_b32_e32 v33, v33, v32
	v_xor_b32_e32 v32, v35, v34
	v_cndmask_b32_e64 v35, v157, -1, vcc
	v_cmp_lt_i32_e32 vcc, -1, v72
	v_and_b32_e32 v34, 0xffffff80, v75
	v_and_b32_e32 v70, 0xffffff80, v72
	v_cndmask_b32_e64 v71, v157, -1, vcc
	v_xor_b32_e32 v35, v35, v34
	v_xor_b32_e32 v34, v71, v70
	v_cmp_lt_i32_e32 vcc, -1, v78
	v_min_u32_e32 v83, v79, v81
	ds_write_b128 v46, v[32:35] offset:32
	v_cndmask_b32_e64 v33, v157, -1, vcc
	v_cmp_lt_i32_e32 vcc, -1, v38
	v_max_u32_e32 v79, v79, v81
	v_and_b32_e32 v32, 0xffffff80, v78
	v_and_b32_e32 v34, 0xffffff80, v38
	v_cndmask_b32_e64 v35, v157, -1, vcc
	v_cmp_lt_i32_e32 vcc, -1, v83
	v_xor_b32_e32 v33, v33, v32
	v_xor_b32_e32 v32, v35, v34
	v_cndmask_b32_e64 v35, v157, -1, vcc
	v_cmp_lt_i32_e32 vcc, -1, v79
	v_and_b32_e32 v34, 0xffffff80, v83
	v_and_b32_e32 v73, 0xffffff80, v79
	v_cndmask_b32_e64 v74, v157, -1, vcc
	v_xor_b32_e32 v35, v35, v34
	v_xor_b32_e32 v34, v74, v73
	ds_write_b128 v46, v[32:35] offset:48
	v_and_b32_sdwa v32, v83, s59 dst_sel:BYTE_1 dst_unused:UNUSED_PAD src0_sel:DWORD src1_sel:DWORD
	v_and_b32_sdwa v71, v78, s59 dst_sel:BYTE_1 dst_unused:UNUSED_PAD src0_sel:DWORD src1_sel:DWORD
	v_bitop3_b16 v32, v79, v32, s59 bitop3:0xec
	v_and_b32_sdwa v70, v75, s59 dst_sel:BYTE_1 dst_unused:UNUSED_PAD src0_sel:DWORD src1_sel:DWORD
	v_bitop3_b16 v33, v38, v71, s59 bitop3:0xec
	v_lshlrev_b32_e32 v32, 16, v32
	v_and_b32_sdwa v67, v67, s59 dst_sel:BYTE_1 dst_unused:UNUSED_PAD src0_sel:DWORD src1_sel:DWORD
	v_or_b32_sdwa v35, v33, v32 dst_sel:DWORD dst_unused:UNUSED_PAD src0_sel:WORD_0 src1_sel:DWORD
	v_bitop3_b16 v33, v72, v70, s59 bitop3:0xec
	v_and_b32_sdwa v69, v69, s59 dst_sel:BYTE_1 dst_unused:UNUSED_PAD src0_sel:DWORD src1_sel:DWORD
	v_bitop3_b16 v32, v37, v67, s59 bitop3:0xec
	v_lshlrev_b32_e32 v33, 16, v33
	v_and_b32_sdwa v48, v48, s59 dst_sel:BYTE_1 dst_unused:UNUSED_PAD src0_sel:DWORD src1_sel:DWORD
	v_or_b32_sdwa v34, v32, v33 dst_sel:DWORD dst_unused:UNUSED_PAD src0_sel:WORD_0 src1_sel:DWORD
	v_bitop3_b16 v33, v66, v69, s59 bitop3:0xec
	v_and_b32_sdwa v45, v45, s59 dst_sel:BYTE_1 dst_unused:UNUSED_PAD src0_sel:DWORD src1_sel:DWORD
	v_bitop3_b16 v32, v39, v48, s59 bitop3:0xec
	v_lshlrev_b32_e32 v33, 16, v33
	v_or_b32_sdwa v33, v32, v33 dst_sel:DWORD dst_unused:UNUSED_PAD src0_sel:WORD_0 src1_sel:DWORD
	v_bitop3_b16 v32, v36, v68, s59 bitop3:0xec
	v_bitop3_b16 v36, v44, v45, s59 bitop3:0xec
	v_lshlrev_b32_e32 v36, 16, v36
	v_or_b32_sdwa v32, v32, v36 dst_sel:DWORD dst_unused:UNUSED_PAD src0_sel:WORD_0 src1_sel:DWORD
	ds_write_b128 v47, v[32:35]
